# v78 + P6 LayerNorm-exchange epilogue: residual row groups 0..3 issued together, 4..6 rolling into freed registers, counted waits (was 8 serialised load-wait-use round trips)
# baseline (speedup 1.0000x reference)
.LBB0_1061:
	v_mov_b32_e32 v132, v192
	v_mov_b32_e32 v133, v191
	s_lshl_b32 s2, s63, 8
	v_add_u32_e32 v200, s50, v133
	s_lshl_b32 s0, s28, 8
	v_add_u32_e32 v174, s2, v200
	s_or_b32 s0, s0, s51
	v_lshl_add_u32 v128, v132, 3, s0
	v_ashrrev_i32_e32 v175, 31, v174
	v_ashrrev_i32_e32 v129, 31, v128
	v_lshlrev_b64 v[130:131], 13, v[174:175]
	v_lshl_add_u64 v[134:135], s[10:11], 0, v[130:131]
	v_lshlrev_b64 v[130:131], 1, v[128:129]
	v_lshl_add_u64 v[138:139], v[134:135], 0, v[130:131]
	v_mov_b64_e32 v[250:251], v[138:139]
	s_mov_b32 s99, 0
	global_load_dwordx4 v[134:137], v[138:139], off
	s_nop 0
	global_load_dwordx4 v[138:141], v[138:139], off offset:256
	s_mov_b32 s98, 0x20000
	v_lshl_add_u64 v[252:253], v[250:251], 0, s[98:99]
	global_load_dwordx4 v[226:229], v[252:253], off
	global_load_dwordx4 v[230:233], v[252:253], off offset:256
	s_mov_b32 s98, 0x40000
	v_lshl_add_u64 v[252:253], v[250:251], 0, s[98:99]
	global_load_dwordx4 v[234:237], v[252:253], off
	global_load_dwordx4 v[238:241], v[252:253], off offset:256
	s_mov_b32 s98, 0x60000
	v_lshl_add_u64 v[252:253], v[250:251], 0, s[98:99]
	global_load_dwordx4 v[242:245], v[252:253], off
	global_load_dwordx4 v[246:249], v[252:253], off offset:256
	v_add_u32_e32 v176, 16, v174
	v_ashrrev_i32_e32 v177, 31, v176
	v_lshlrev_b64 v[142:143], 13, v[176:177]
	v_lshl_add_u64 v[142:143], s[10:11], 0, v[142:143]
	v_lshl_add_u64 v[142:143], v[142:143], 0, v[130:131]
	v_add_u32_e32 v172, 32, v174
	v_ashrrev_i32_e32 v173, 31, v172
	v_add_u32_e32 v178, 48, v174
	v_ashrrev_i32_e32 v179, 31, v178
	v_add_u32_e32 v180, 0x80, v174
	v_ashrrev_i32_e32 v181, 31, v180
	v_add_u32_e32 v182, 0x90, v174
	v_ashrrev_i32_e32 v183, 31, v182
	v_add_u32_e32 v184, 0xa0, v174
	v_ashrrev_i32_e32 v185, 31, v184
	v_add_u32_e32 v186, 0xb0, v174
	v_ashrrev_i32_e32 v187, 31, v186
	v_cmp_eq_u32_e32 vcc, 0, v132
	s_waitcnt vmcnt(6)
	v_cvt_f32_i32_sdwa v145, sext(v135) dst_sel:DWORD dst_unused:UNUSED_PAD src0_sel:WORD_1
	v_cvt_f32_i32_sdwa v144, sext(v135) dst_sel:DWORD dst_unused:UNUSED_PAD src0_sel:WORD_0
	v_cvt_f32_i32_sdwa v135, sext(v134) dst_sel:DWORD dst_unused:UNUSED_PAD src0_sel:WORD_1
	v_cvt_f32_i32_sdwa v134, sext(v134) dst_sel:DWORD dst_unused:UNUSED_PAD src0_sel:WORD_0
	v_cvt_f32_i32_sdwa v147, sext(v137) dst_sel:DWORD dst_unused:UNUSED_PAD src0_sel:WORD_1
	v_cvt_f32_i32_sdwa v146, sext(v137) dst_sel:DWORD dst_unused:UNUSED_PAD src0_sel:WORD_0
	v_cvt_f32_i32_sdwa v137, sext(v136) dst_sel:DWORD dst_unused:UNUSED_PAD src0_sel:WORD_1
	v_cvt_f32_i32_sdwa v136, sext(v136) dst_sel:DWORD dst_unused:UNUSED_PAD src0_sel:WORD_0
	v_cvt_f32_i32_sdwa v149, sext(v139) dst_sel:DWORD dst_unused:UNUSED_PAD src0_sel:WORD_1
	v_cvt_f32_i32_sdwa v148, sext(v139) dst_sel:DWORD dst_unused:UNUSED_PAD src0_sel:WORD_0
	v_cvt_f32_i32_sdwa v139, sext(v138) dst_sel:DWORD dst_unused:UNUSED_PAD src0_sel:WORD_1
	v_cvt_f32_i32_sdwa v138, sext(v138) dst_sel:DWORD dst_unused:UNUSED_PAD src0_sel:WORD_0
	v_cvt_f32_i32_sdwa v151, sext(v141) dst_sel:DWORD dst_unused:UNUSED_PAD src0_sel:WORD_1
	v_cvt_f32_i32_sdwa v150, sext(v141) dst_sel:DWORD dst_unused:UNUSED_PAD src0_sel:WORD_0
	v_cvt_f32_i32_sdwa v141, sext(v140) dst_sel:DWORD dst_unused:UNUSED_PAD src0_sel:WORD_1
	v_cvt_f32_i32_sdwa v140, sext(v140) dst_sel:DWORD dst_unused:UNUSED_PAD src0_sel:WORD_0
	v_pk_mul_f32 v[134:135], v[134:135], s[24:25] op_sel_hi:[1,0]
	v_pk_mul_f32 v[144:145], v[144:145], s[24:25] op_sel_hi:[1,0]
	v_pk_mul_f32 v[136:137], v[136:137], s[24:25] op_sel_hi:[1,0]
	v_pk_mul_f32 v[146:147], v[146:147], s[24:25] op_sel_hi:[1,0]
	v_pk_mul_f32 v[138:139], v[138:139], s[24:25] op_sel_hi:[1,0]
	v_pk_mul_f32 v[148:149], v[148:149], s[24:25] op_sel_hi:[1,0]
	v_pk_mul_f32 v[140:141], v[140:141], s[24:25] op_sel_hi:[1,0]
	v_pk_mul_f32 v[150:151], v[150:151], s[24:25] op_sel_hi:[1,0]
	v_pk_fma_f32 v[14:15], v[144:145], s[26:27], v[14:15] op_sel_hi:[1,0,1]
	v_pk_fma_f32 v[12:13], v[134:135], s[26:27], v[12:13] op_sel_hi:[1,0,1]
	v_pk_fma_f32 v[10:11], v[146:147], s[26:27], v[10:11] op_sel_hi:[1,0,1]
	v_pk_fma_f32 v[8:9], v[136:137], s[26:27], v[8:9] op_sel_hi:[1,0,1]
	v_pk_fma_f32 v[6:7], v[148:149], s[26:27], v[6:7] op_sel_hi:[1,0,1]
	v_pk_fma_f32 v[4:5], v[138:139], s[26:27], v[4:5] op_sel_hi:[1,0,1]
	v_pk_fma_f32 v[2:3], v[150:151], s[26:27], v[2:3] op_sel_hi:[1,0,1]
	v_pk_fma_f32 v[0:1], v[140:141], s[26:27], v[0:1] op_sel_hi:[1,0,1]
	s_nop 0
	s_mov_b32 s98, 0x100000
	v_lshl_add_u64 v[252:253], v[250:251], 0, s[98:99]
	global_load_dwordx4 v[134:137], v[252:253], off
	global_load_dwordx4 v[138:141], v[252:253], off offset:256
	v_lshlrev_b64 v[142:143], 13, v[172:173]
	v_lshl_add_u64 v[142:143], s[10:11], 0, v[142:143]
	v_lshl_add_u64 v[142:143], v[142:143], 0, v[130:131]
	s_waitcnt vmcnt(7)
	v_cvt_f32_i32_sdwa v145, sext(v227) dst_sel:DWORD dst_unused:UNUSED_PAD src0_sel:WORD_1
	v_cvt_f32_i32_sdwa v144, sext(v227) dst_sel:DWORD dst_unused:UNUSED_PAD src0_sel:WORD_0
	v_cvt_f32_i32_sdwa v227, sext(v226) dst_sel:DWORD dst_unused:UNUSED_PAD src0_sel:WORD_1
	v_cvt_f32_i32_sdwa v226, sext(v226) dst_sel:DWORD dst_unused:UNUSED_PAD src0_sel:WORD_0
	v_cvt_f32_i32_sdwa v147, sext(v229) dst_sel:DWORD dst_unused:UNUSED_PAD src0_sel:WORD_1
	v_cvt_f32_i32_sdwa v146, sext(v229) dst_sel:DWORD dst_unused:UNUSED_PAD src0_sel:WORD_0
	v_cvt_f32_i32_sdwa v229, sext(v228) dst_sel:DWORD dst_unused:UNUSED_PAD src0_sel:WORD_1
	v_cvt_f32_i32_sdwa v228, sext(v228) dst_sel:DWORD dst_unused:UNUSED_PAD src0_sel:WORD_0
	s_waitcnt vmcnt(6)
	v_cvt_f32_i32_sdwa v149, sext(v231) dst_sel:DWORD dst_unused:UNUSED_PAD src0_sel:WORD_1
	v_cvt_f32_i32_sdwa v148, sext(v231) dst_sel:DWORD dst_unused:UNUSED_PAD src0_sel:WORD_0
	v_cvt_f32_i32_sdwa v231, sext(v230) dst_sel:DWORD dst_unused:UNUSED_PAD src0_sel:WORD_1
	v_cvt_f32_i32_sdwa v230, sext(v230) dst_sel:DWORD dst_unused:UNUSED_PAD src0_sel:WORD_0
	v_cvt_f32_i32_sdwa v151, sext(v233) dst_sel:DWORD dst_unused:UNUSED_PAD src0_sel:WORD_1
	v_cvt_f32_i32_sdwa v150, sext(v233) dst_sel:DWORD dst_unused:UNUSED_PAD src0_sel:WORD_0
	v_cvt_f32_i32_sdwa v233, sext(v232) dst_sel:DWORD dst_unused:UNUSED_PAD src0_sel:WORD_1
	v_cvt_f32_i32_sdwa v232, sext(v232) dst_sel:DWORD dst_unused:UNUSED_PAD src0_sel:WORD_0
	v_pk_mul_f32 v[226:227], v[226:227], s[24:25] op_sel_hi:[1,0]
	v_pk_mul_f32 v[144:145], v[144:145], s[24:25] op_sel_hi:[1,0]
	v_pk_mul_f32 v[228:229], v[228:229], s[24:25] op_sel_hi:[1,0]
	v_pk_mul_f32 v[146:147], v[146:147], s[24:25] op_sel_hi:[1,0]
	v_pk_mul_f32 v[230:231], v[230:231], s[24:25] op_sel_hi:[1,0]
	v_pk_mul_f32 v[148:149], v[148:149], s[24:25] op_sel_hi:[1,0]
	v_pk_mul_f32 v[232:233], v[232:233], s[24:25] op_sel_hi:[1,0]
	v_pk_mul_f32 v[150:151], v[150:151], s[24:25] op_sel_hi:[1,0]
	v_pk_fma_f32 v[38:39], v[144:145], s[26:27], v[38:39] op_sel_hi:[1,0,1]
	v_pk_fma_f32 v[36:37], v[226:227], s[26:27], v[36:37] op_sel_hi:[1,0,1]
	v_pk_fma_f32 v[34:35], v[146:147], s[26:27], v[34:35] op_sel_hi:[1,0,1]
	v_pk_fma_f32 v[32:33], v[228:229], s[26:27], v[32:33] op_sel_hi:[1,0,1]
	v_pk_fma_f32 v[26:27], v[148:149], s[26:27], v[26:27] op_sel_hi:[1,0,1]
	v_pk_fma_f32 v[24:25], v[230:231], s[26:27], v[24:25] op_sel_hi:[1,0,1]
	v_pk_fma_f32 v[18:19], v[150:151], s[26:27], v[18:19] op_sel_hi:[1,0,1]
	v_pk_fma_f32 v[16:17], v[232:233], s[26:27], v[16:17] op_sel_hi:[1,0,1]
	s_nop 0
	s_mov_b32 s98, 0x120000
	v_lshl_add_u64 v[252:253], v[250:251], 0, s[98:99]
	global_load_dwordx4 v[226:229], v[252:253], off
	global_load_dwordx4 v[230:233], v[252:253], off offset:256
	v_lshlrev_b64 v[142:143], 13, v[178:179]
	v_lshl_add_u64 v[142:143], s[10:11], 0, v[142:143]
	v_lshl_add_u64 v[142:143], v[142:143], 0, v[130:131]
	s_waitcnt vmcnt(7)
	v_cvt_f32_i32_sdwa v145, sext(v235) dst_sel:DWORD dst_unused:UNUSED_PAD src0_sel:WORD_1
	v_cvt_f32_i32_sdwa v144, sext(v235) dst_sel:DWORD dst_unused:UNUSED_PAD src0_sel:WORD_0
	v_cvt_f32_i32_sdwa v235, sext(v234) dst_sel:DWORD dst_unused:UNUSED_PAD src0_sel:WORD_1
	v_cvt_f32_i32_sdwa v234, sext(v234) dst_sel:DWORD dst_unused:UNUSED_PAD src0_sel:WORD_0
	v_cvt_f32_i32_sdwa v147, sext(v237) dst_sel:DWORD dst_unused:UNUSED_PAD src0_sel:WORD_1
	v_cvt_f32_i32_sdwa v146, sext(v237) dst_sel:DWORD dst_unused:UNUSED_PAD src0_sel:WORD_0
	v_cvt_f32_i32_sdwa v237, sext(v236) dst_sel:DWORD dst_unused:UNUSED_PAD src0_sel:WORD_1
	v_cvt_f32_i32_sdwa v236, sext(v236) dst_sel:DWORD dst_unused:UNUSED_PAD src0_sel:WORD_0
	s_waitcnt vmcnt(6)
	v_cvt_f32_i32_sdwa v149, sext(v239) dst_sel:DWORD dst_unused:UNUSED_PAD src0_sel:WORD_1
	v_cvt_f32_i32_sdwa v148, sext(v239) dst_sel:DWORD dst_unused:UNUSED_PAD src0_sel:WORD_0
	v_cvt_f32_i32_sdwa v239, sext(v238) dst_sel:DWORD dst_unused:UNUSED_PAD src0_sel:WORD_1
	v_cvt_f32_i32_sdwa v238, sext(v238) dst_sel:DWORD dst_unused:UNUSED_PAD src0_sel:WORD_0
	v_cvt_f32_i32_sdwa v151, sext(v241) dst_sel:DWORD dst_unused:UNUSED_PAD src0_sel:WORD_1
	v_cvt_f32_i32_sdwa v150, sext(v241) dst_sel:DWORD dst_unused:UNUSED_PAD src0_sel:WORD_0
	v_cvt_f32_i32_sdwa v241, sext(v240) dst_sel:DWORD dst_unused:UNUSED_PAD src0_sel:WORD_1
	v_cvt_f32_i32_sdwa v240, sext(v240) dst_sel:DWORD dst_unused:UNUSED_PAD src0_sel:WORD_0
	v_pk_mul_f32 v[234:235], v[234:235], s[24:25] op_sel_hi:[1,0]
	v_pk_mul_f32 v[144:145], v[144:145], s[24:25] op_sel_hi:[1,0]
	v_pk_mul_f32 v[236:237], v[236:237], s[24:25] op_sel_hi:[1,0]
	v_pk_mul_f32 v[146:147], v[146:147], s[24:25] op_sel_hi:[1,0]
	v_pk_mul_f32 v[238:239], v[238:239], s[24:25] op_sel_hi:[1,0]
	v_pk_mul_f32 v[148:149], v[148:149], s[24:25] op_sel_hi:[1,0]
	v_pk_mul_f32 v[240:241], v[240:241], s[24:25] op_sel_hi:[1,0]
	v_pk_mul_f32 v[150:151], v[150:151], s[24:25] op_sel_hi:[1,0]
	v_pk_fma_f32 v[46:47], v[144:145], s[26:27], v[46:47] op_sel_hi:[1,0,1]
	v_pk_fma_f32 v[44:45], v[234:235], s[26:27], v[44:45] op_sel_hi:[1,0,1]
	v_pk_fma_f32 v[42:43], v[146:147], s[26:27], v[42:43] op_sel_hi:[1,0,1]
	v_pk_fma_f32 v[40:41], v[236:237], s[26:27], v[40:41] op_sel_hi:[1,0,1]
	v_pk_fma_f32 v[30:31], v[148:149], s[26:27], v[30:31] op_sel_hi:[1,0,1]
	v_pk_fma_f32 v[28:29], v[238:239], s[26:27], v[28:29] op_sel_hi:[1,0,1]
	v_pk_fma_f32 v[22:23], v[150:151], s[26:27], v[22:23] op_sel_hi:[1,0,1]
	v_pk_fma_f32 v[20:21], v[240:241], s[26:27], v[20:21] op_sel_hi:[1,0,1]
	s_nop 0
	s_mov_b32 s98, 0x140000
	v_lshl_add_u64 v[252:253], v[250:251], 0, s[98:99]
	global_load_dwordx4 v[234:237], v[252:253], off
	global_load_dwordx4 v[238:241], v[252:253], off offset:256
	v_lshlrev_b64 v[142:143], 13, v[180:181]
	v_lshl_add_u64 v[142:143], s[10:11], 0, v[142:143]
	v_lshl_add_u64 v[142:143], v[142:143], 0, v[130:131]
	s_waitcnt vmcnt(7)
	v_cvt_f32_i32_sdwa v145, sext(v243) dst_sel:DWORD dst_unused:UNUSED_PAD src0_sel:WORD_1
	v_cvt_f32_i32_sdwa v144, sext(v243) dst_sel:DWORD dst_unused:UNUSED_PAD src0_sel:WORD_0
	v_cvt_f32_i32_sdwa v243, sext(v242) dst_sel:DWORD dst_unused:UNUSED_PAD src0_sel:WORD_1
	v_cvt_f32_i32_sdwa v242, sext(v242) dst_sel:DWORD dst_unused:UNUSED_PAD src0_sel:WORD_0
	v_cvt_f32_i32_sdwa v147, sext(v245) dst_sel:DWORD dst_unused:UNUSED_PAD src0_sel:WORD_1
	v_cvt_f32_i32_sdwa v146, sext(v245) dst_sel:DWORD dst_unused:UNUSED_PAD src0_sel:WORD_0
	v_cvt_f32_i32_sdwa v245, sext(v244) dst_sel:DWORD dst_unused:UNUSED_PAD src0_sel:WORD_1
	v_cvt_f32_i32_sdwa v244, sext(v244) dst_sel:DWORD dst_unused:UNUSED_PAD src0_sel:WORD_0
	s_waitcnt vmcnt(6)
	v_cvt_f32_i32_sdwa v149, sext(v247) dst_sel:DWORD dst_unused:UNUSED_PAD src0_sel:WORD_1
	v_cvt_f32_i32_sdwa v148, sext(v247) dst_sel:DWORD dst_unused:UNUSED_PAD src0_sel:WORD_0
	v_cvt_f32_i32_sdwa v247, sext(v246) dst_sel:DWORD dst_unused:UNUSED_PAD src0_sel:WORD_1
	v_cvt_f32_i32_sdwa v246, sext(v246) dst_sel:DWORD dst_unused:UNUSED_PAD src0_sel:WORD_0
	v_cvt_f32_i32_sdwa v151, sext(v249) dst_sel:DWORD dst_unused:UNUSED_PAD src0_sel:WORD_1
	v_cvt_f32_i32_sdwa v150, sext(v249) dst_sel:DWORD dst_unused:UNUSED_PAD src0_sel:WORD_0
	v_cvt_f32_i32_sdwa v249, sext(v248) dst_sel:DWORD dst_unused:UNUSED_PAD src0_sel:WORD_1
	v_cvt_f32_i32_sdwa v248, sext(v248) dst_sel:DWORD dst_unused:UNUSED_PAD src0_sel:WORD_0
	v_pk_mul_f32 v[242:243], v[242:243], s[24:25] op_sel_hi:[1,0]
	v_pk_mul_f32 v[144:145], v[144:145], s[24:25] op_sel_hi:[1,0]
	v_pk_mul_f32 v[244:245], v[244:245], s[24:25] op_sel_hi:[1,0]
	v_pk_mul_f32 v[146:147], v[146:147], s[24:25] op_sel_hi:[1,0]
	v_pk_mul_f32 v[246:247], v[246:247], s[24:25] op_sel_hi:[1,0]
	v_pk_mul_f32 v[148:149], v[148:149], s[24:25] op_sel_hi:[1,0]
	v_pk_mul_f32 v[248:249], v[248:249], s[24:25] op_sel_hi:[1,0]
	v_pk_mul_f32 v[150:151], v[150:151], s[24:25] op_sel_hi:[1,0]
	v_pk_fma_f32 v[66:67], v[144:145], s[26:27], v[66:67] op_sel_hi:[1,0,1]
	v_pk_fma_f32 v[64:65], v[242:243], s[26:27], v[64:65] op_sel_hi:[1,0,1]
	v_pk_fma_f32 v[58:59], v[146:147], s[26:27], v[58:59] op_sel_hi:[1,0,1]
	v_pk_fma_f32 v[56:57], v[244:245], s[26:27], v[56:57] op_sel_hi:[1,0,1]
	v_pk_fma_f32 v[54:55], v[148:149], s[26:27], v[54:55] op_sel_hi:[1,0,1]
	v_pk_fma_f32 v[52:53], v[246:247], s[26:27], v[52:53] op_sel_hi:[1,0,1]
	v_pk_fma_f32 v[50:51], v[150:151], s[26:27], v[50:51] op_sel_hi:[1,0,1]
	v_pk_fma_f32 v[48:49], v[248:249], s[26:27], v[48:49] op_sel_hi:[1,0,1]
	s_nop 0
	v_lshlrev_b64 v[142:143], 13, v[182:183]
	v_lshl_add_u64 v[142:143], s[10:11], 0, v[142:143]
	v_lshl_add_u64 v[142:143], v[142:143], 0, v[130:131]
	s_waitcnt vmcnt(5)
	v_cvt_f32_i32_sdwa v145, sext(v135) dst_sel:DWORD dst_unused:UNUSED_PAD src0_sel:WORD_1
	v_cvt_f32_i32_sdwa v144, sext(v135) dst_sel:DWORD dst_unused:UNUSED_PAD src0_sel:WORD_0
	v_cvt_f32_i32_sdwa v135, sext(v134) dst_sel:DWORD dst_unused:UNUSED_PAD src0_sel:WORD_1
	v_cvt_f32_i32_sdwa v134, sext(v134) dst_sel:DWORD dst_unused:UNUSED_PAD src0_sel:WORD_0
	v_cvt_f32_i32_sdwa v147, sext(v137) dst_sel:DWORD dst_unused:UNUSED_PAD src0_sel:WORD_1
	v_cvt_f32_i32_sdwa v146, sext(v137) dst_sel:DWORD dst_unused:UNUSED_PAD src0_sel:WORD_0
	v_cvt_f32_i32_sdwa v137, sext(v136) dst_sel:DWORD dst_unused:UNUSED_PAD src0_sel:WORD_1
	v_cvt_f32_i32_sdwa v136, sext(v136) dst_sel:DWORD dst_unused:UNUSED_PAD src0_sel:WORD_0
	s_waitcnt vmcnt(4)
	v_cvt_f32_i32_sdwa v149, sext(v139) dst_sel:DWORD dst_unused:UNUSED_PAD src0_sel:WORD_1
	v_cvt_f32_i32_sdwa v148, sext(v139) dst_sel:DWORD dst_unused:UNUSED_PAD src0_sel:WORD_0
	v_cvt_f32_i32_sdwa v139, sext(v138) dst_sel:DWORD dst_unused:UNUSED_PAD src0_sel:WORD_1
	v_cvt_f32_i32_sdwa v138, sext(v138) dst_sel:DWORD dst_unused:UNUSED_PAD src0_sel:WORD_0
	v_cvt_f32_i32_sdwa v151, sext(v141) dst_sel:DWORD dst_unused:UNUSED_PAD src0_sel:WORD_1
	v_cvt_f32_i32_sdwa v150, sext(v141) dst_sel:DWORD dst_unused:UNUSED_PAD src0_sel:WORD_0
	v_cvt_f32_i32_sdwa v141, sext(v140) dst_sel:DWORD dst_unused:UNUSED_PAD src0_sel:WORD_1
	v_cvt_f32_i32_sdwa v140, sext(v140) dst_sel:DWORD dst_unused:UNUSED_PAD src0_sel:WORD_0
	v_pk_mul_f32 v[134:135], v[134:135], s[24:25] op_sel_hi:[1,0]
	v_pk_mul_f32 v[144:145], v[144:145], s[24:25] op_sel_hi:[1,0]
	v_pk_mul_f32 v[136:137], v[136:137], s[24:25] op_sel_hi:[1,0]
	v_pk_mul_f32 v[146:147], v[146:147], s[24:25] op_sel_hi:[1,0]
	v_pk_mul_f32 v[138:139], v[138:139], s[24:25] op_sel_hi:[1,0]
	v_pk_mul_f32 v[148:149], v[148:149], s[24:25] op_sel_hi:[1,0]
	v_pk_mul_f32 v[140:141], v[140:141], s[24:25] op_sel_hi:[1,0]
	v_pk_mul_f32 v[150:151], v[150:151], s[24:25] op_sel_hi:[1,0]
	v_pk_fma_f32 v[78:79], v[144:145], s[26:27], v[78:79] op_sel_hi:[1,0,1]
	v_pk_fma_f32 v[76:77], v[134:135], s[26:27], v[76:77] op_sel_hi:[1,0,1]
	v_pk_fma_f32 v[74:75], v[146:147], s[26:27], v[74:75] op_sel_hi:[1,0,1]
	v_pk_fma_f32 v[72:73], v[136:137], s[26:27], v[72:73] op_sel_hi:[1,0,1]
	v_pk_fma_f32 v[70:71], v[148:149], s[26:27], v[70:71] op_sel_hi:[1,0,1]
	v_pk_fma_f32 v[68:69], v[138:139], s[26:27], v[68:69] op_sel_hi:[1,0,1]
	v_pk_fma_f32 v[62:63], v[150:151], s[26:27], v[62:63] op_sel_hi:[1,0,1]
	v_pk_fma_f32 v[60:61], v[140:141], s[26:27], v[60:61] op_sel_hi:[1,0,1]
	s_nop 0
	v_lshlrev_b64 v[142:143], 13, v[184:185]
	v_lshl_add_u64 v[142:143], s[10:11], 0, v[142:143]
	v_lshl_add_u64 v[142:143], v[142:143], 0, v[130:131]
	s_waitcnt vmcnt(3)
	v_cvt_f32_i32_sdwa v145, sext(v227) dst_sel:DWORD dst_unused:UNUSED_PAD src0_sel:WORD_1
	v_cvt_f32_i32_sdwa v144, sext(v227) dst_sel:DWORD dst_unused:UNUSED_PAD src0_sel:WORD_0
	v_cvt_f32_i32_sdwa v227, sext(v226) dst_sel:DWORD dst_unused:UNUSED_PAD src0_sel:WORD_1
	v_cvt_f32_i32_sdwa v226, sext(v226) dst_sel:DWORD dst_unused:UNUSED_PAD src0_sel:WORD_0
	v_cvt_f32_i32_sdwa v147, sext(v229) dst_sel:DWORD dst_unused:UNUSED_PAD src0_sel:WORD_1
	v_cvt_f32_i32_sdwa v146, sext(v229) dst_sel:DWORD dst_unused:UNUSED_PAD src0_sel:WORD_0
	v_cvt_f32_i32_sdwa v229, sext(v228) dst_sel:DWORD dst_unused:UNUSED_PAD src0_sel:WORD_1
	v_cvt_f32_i32_sdwa v228, sext(v228) dst_sel:DWORD dst_unused:UNUSED_PAD src0_sel:WORD_0
	s_waitcnt vmcnt(2)
	v_cvt_f32_i32_sdwa v149, sext(v231) dst_sel:DWORD dst_unused:UNUSED_PAD src0_sel:WORD_1
	v_cvt_f32_i32_sdwa v148, sext(v231) dst_sel:DWORD dst_unused:UNUSED_PAD src0_sel:WORD_0
	v_cvt_f32_i32_sdwa v231, sext(v230) dst_sel:DWORD dst_unused:UNUSED_PAD src0_sel:WORD_1
	v_cvt_f32_i32_sdwa v230, sext(v230) dst_sel:DWORD dst_unused:UNUSED_PAD src0_sel:WORD_0
	v_cvt_f32_i32_sdwa v151, sext(v233) dst_sel:DWORD dst_unused:UNUSED_PAD src0_sel:WORD_1
	v_cvt_f32_i32_sdwa v150, sext(v233) dst_sel:DWORD dst_unused:UNUSED_PAD src0_sel:WORD_0
	v_cvt_f32_i32_sdwa v233, sext(v232) dst_sel:DWORD dst_unused:UNUSED_PAD src0_sel:WORD_1
	v_cvt_f32_i32_sdwa v232, sext(v232) dst_sel:DWORD dst_unused:UNUSED_PAD src0_sel:WORD_0
	v_pk_mul_f32 v[226:227], v[226:227], s[24:25] op_sel_hi:[1,0]
	v_pk_mul_f32 v[144:145], v[144:145], s[24:25] op_sel_hi:[1,0]
	v_pk_mul_f32 v[228:229], v[228:229], s[24:25] op_sel_hi:[1,0]
	v_pk_mul_f32 v[146:147], v[146:147], s[24:25] op_sel_hi:[1,0]
	v_pk_mul_f32 v[230:231], v[230:231], s[24:25] op_sel_hi:[1,0]
	v_pk_mul_f32 v[148:149], v[148:149], s[24:25] op_sel_hi:[1,0]
	v_pk_mul_f32 v[232:233], v[232:233], s[24:25] op_sel_hi:[1,0]
	v_pk_mul_f32 v[150:151], v[150:151], s[24:25] op_sel_hi:[1,0]
	v_pk_fma_f32 v[94:95], v[144:145], s[26:27], v[94:95] op_sel_hi:[1,0,1]
	v_pk_fma_f32 v[92:93], v[226:227], s[26:27], v[92:93] op_sel_hi:[1,0,1]
	v_pk_fma_f32 v[90:91], v[146:147], s[26:27], v[90:91] op_sel_hi:[1,0,1]
	v_pk_fma_f32 v[88:89], v[228:229], s[26:27], v[88:89] op_sel_hi:[1,0,1]
	v_pk_fma_f32 v[86:87], v[148:149], s[26:27], v[86:87] op_sel_hi:[1,0,1]
	v_pk_fma_f32 v[84:85], v[230:231], s[26:27], v[84:85] op_sel_hi:[1,0,1]
	v_pk_fma_f32 v[82:83], v[150:151], s[26:27], v[82:83] op_sel_hi:[1,0,1]
	v_pk_fma_f32 v[80:81], v[232:233], s[26:27], v[80:81] op_sel_hi:[1,0,1]
	v_mov_b32_e32 v144, v13
	v_lshlrev_b64 v[142:143], 13, v[186:187]
	v_lshl_add_u64 v[142:143], s[10:11], 0, v[142:143]
	v_lshl_add_u64 v[130:131], v[142:143], 0, v[130:131]
	v_mov_b32_e32 v145, v14
	v_mov_b32_e32 v146, v12
	v_mov_b32_e32 v147, v15
	v_pk_add_f32 v[144:145], v[144:145], v[146:147]
	s_waitcnt vmcnt(1)
	v_cvt_f32_i32_sdwa v143, sext(v235) dst_sel:DWORD dst_unused:UNUSED_PAD src0_sel:WORD_1
	v_cvt_f32_i32_sdwa v142, sext(v235) dst_sel:DWORD dst_unused:UNUSED_PAD src0_sel:WORD_0
	v_cvt_f32_i32_sdwa v235, sext(v234) dst_sel:DWORD dst_unused:UNUSED_PAD src0_sel:WORD_1
	v_cvt_f32_i32_sdwa v234, sext(v234) dst_sel:DWORD dst_unused:UNUSED_PAD src0_sel:WORD_0
	v_cvt_f32_i32_sdwa v149, sext(v237) dst_sel:DWORD dst_unused:UNUSED_PAD src0_sel:WORD_1
	v_cvt_f32_i32_sdwa v148, sext(v237) dst_sel:DWORD dst_unused:UNUSED_PAD src0_sel:WORD_0
	v_cvt_f32_i32_sdwa v237, sext(v236) dst_sel:DWORD dst_unused:UNUSED_PAD src0_sel:WORD_1
	v_cvt_f32_i32_sdwa v236, sext(v236) dst_sel:DWORD dst_unused:UNUSED_PAD src0_sel:WORD_0
	s_waitcnt vmcnt(0)
	v_cvt_f32_i32_sdwa v151, sext(v239) dst_sel:DWORD dst_unused:UNUSED_PAD src0_sel:WORD_1
	v_cvt_f32_i32_sdwa v150, sext(v239) dst_sel:DWORD dst_unused:UNUSED_PAD src0_sel:WORD_0
	v_cvt_f32_i32_sdwa v239, sext(v238) dst_sel:DWORD dst_unused:UNUSED_PAD src0_sel:WORD_1
	v_cvt_f32_i32_sdwa v238, sext(v238) dst_sel:DWORD dst_unused:UNUSED_PAD src0_sel:WORD_0
	v_cvt_f32_i32_sdwa v153, sext(v241) dst_sel:DWORD dst_unused:UNUSED_PAD src0_sel:WORD_1
	v_cvt_f32_i32_sdwa v152, sext(v241) dst_sel:DWORD dst_unused:UNUSED_PAD src0_sel:WORD_0
	v_cvt_f32_i32_sdwa v241, sext(v240) dst_sel:DWORD dst_unused:UNUSED_PAD src0_sel:WORD_1
	v_cvt_f32_i32_sdwa v240, sext(v240) dst_sel:DWORD dst_unused:UNUSED_PAD src0_sel:WORD_0
	v_pk_mul_f32 v[234:235], v[234:235], s[24:25] op_sel_hi:[1,0]
	v_pk_mul_f32 v[142:143], v[142:143], s[24:25] op_sel_hi:[1,0]
	v_pk_mul_f32 v[236:237], v[236:237], s[24:25] op_sel_hi:[1,0]
	v_pk_mul_f32 v[148:149], v[148:149], s[24:25] op_sel_hi:[1,0]
	v_pk_mul_f32 v[238:239], v[238:239], s[24:25] op_sel_hi:[1,0]
	v_pk_mul_f32 v[150:151], v[150:151], s[24:25] op_sel_hi:[1,0]
	v_pk_mul_f32 v[240:241], v[240:241], s[24:25] op_sel_hi:[1,0]
	v_pk_mul_f32 v[152:153], v[152:153], s[24:25] op_sel_hi:[1,0]
	v_pk_fma_f32 v[110:111], v[142:143], s[26:27], v[110:111] op_sel_hi:[1,0,1]
	v_pk_fma_f32 v[108:109], v[234:235], s[26:27], v[108:109] op_sel_hi:[1,0,1]
	v_pk_fma_f32 v[106:107], v[148:149], s[26:27], v[106:107] op_sel_hi:[1,0,1]
	v_pk_fma_f32 v[104:105], v[236:237], s[26:27], v[104:105] op_sel_hi:[1,0,1]
	v_pk_fma_f32 v[102:103], v[150:151], s[26:27], v[102:103] op_sel_hi:[1,0,1]
	v_pk_fma_f32 v[100:101], v[238:239], s[26:27], v[100:101] op_sel_hi:[1,0,1]
	v_pk_fma_f32 v[98:99], v[152:153], s[26:27], v[98:99] op_sel_hi:[1,0,1]
	v_pk_fma_f32 v[96:97], v[240:241], s[26:27], v[96:97] op_sel_hi:[1,0,1]
	v_mov_b32_e32 v134, v9
	global_load_dwordx4 v[136:139], v[130:131], off
	global_load_dwordx4 v[140:143], v[130:131], off offset:256
	v_mov_b32_e32 v135, v10
	v_mov_b32_e32 v148, v8
	v_mov_b32_e32 v149, v11
	v_pk_add_f32 v[134:135], v[134:135], v[148:149]
	v_add_f32_e32 v131, v144, v145
	v_pk_add_f32 v[134:135], v[134:135], v[134:135] op_sel_hi:[0,1]
	v_add_f32_e32 v151, v4, v5
	v_add_f32_e32 v153, v6, v7
	v_mov_b32_e32 v150, v0
	v_mov_b32_e32 v152, v1
	v_mov_b32_e32 v130, v3
	v_add_f32_e32 v131, 0, v131
	v_mov_b32_e32 v134, v2
	v_pk_add_f32 v[146:147], v[150:151], v[152:153]
	v_pk_add_f32 v[130:131], v[134:135], v[130:131]
	s_nop 0
	v_pk_add_f32 v[130:131], v[146:147], v[130:131]
	s_nop 0
	v_add_f32_e32 v130, v130, v131
	ds_bpermute_b32 v131, v218, v130
	s_waitcnt lgkmcnt(0)
	v_add_f32_e32 v130, v130, v131
	ds_bpermute_b32 v131, v219, v130
	s_waitcnt lgkmcnt(0)
	v_add_f32_e32 v131, v130, v131
	v_fmamk_f32 v134, v131, 0xbc800000, v15
	v_fmamk_f32 v144, v131, 0xbc800000, v13
	v_fmamk_f32 v146, v131, 0xbc800000, v11
	v_fmamk_f32 v148, v131, 0xbc800000, v9
	v_fmamk_f32 v130, v131, 0xbc800000, v14
	v_fmamk_f32 v135, v131, 0xbc800000, v12
	v_fmamk_f32 v145, v131, 0xbc800000, v10
	v_fmamk_f32 v147, v131, 0xbc800000, v8
	v_fmamk_f32 v150, v131, 0xbc800000, v7
	v_fmamk_f32 v152, v131, 0xbc800000, v5
	v_mul_f32_e32 v144, v144, v144
	v_mul_f32_e32 v134, v134, v134
	v_mul_f32_e32 v148, v148, v148
	v_mul_f32_e32 v146, v146, v146
	v_fmamk_f32 v149, v131, 0xbc800000, v6
	v_fmamk_f32 v151, v131, 0xbc800000, v4
	v_fmamk_f32 v154, v131, 0xbc800000, v3
	v_fmamk_f32 v156, v131, 0xbc800000, v1
	v_mul_f32_e32 v152, v152, v152
	v_mul_f32_e32 v150, v150, v150
	v_fmac_f32_e32 v144, v135, v135
	v_fmac_f32_e32 v134, v130, v130
	v_fmac_f32_e32 v148, v147, v147
	v_fmac_f32_e32 v146, v145, v145
	v_fmamk_f32 v153, v131, 0xbc800000, v2
	v_fmamk_f32 v155, v131, 0xbc800000, v0
	v_mul_f32_e32 v156, v156, v156
	v_mul_f32_e32 v154, v154, v154
	v_fmac_f32_e32 v152, v151, v151
	v_fmac_f32_e32 v150, v149, v149
	v_add_f32_e32 v130, v144, v134
	v_add_f32_e32 v134, v148, v146
	v_fmac_f32_e32 v156, v155, v155
	v_fmac_f32_e32 v154, v153, v153
	v_add_f32_e32 v135, v152, v150
	v_add_f32_e32 v130, v130, v134
	v_add_f32_e32 v144, v156, v154
	v_add_f32_e32 v130, v135, v130
	v_add_f32_e32 v130, v144, v130
	ds_bpermute_b32 v134, v218, v130
	s_waitcnt lgkmcnt(0)
	v_add_f32_e32 v134, v130, v134
	ds_bpermute_b32 v135, v219, v134
	v_lshl_add_u32 v130, v200, 5, s59
	s_waitcnt vmcnt(1)
	v_cvt_f32_i32_sdwa v145, sext(v137) dst_sel:DWORD dst_unused:UNUSED_PAD src0_sel:WORD_1
	v_cvt_f32_i32_sdwa v144, sext(v137) dst_sel:DWORD dst_unused:UNUSED_PAD src0_sel:WORD_0
	v_cvt_f32_i32_sdwa v137, sext(v136) dst_sel:DWORD dst_unused:UNUSED_PAD src0_sel:WORD_1
	v_cvt_f32_i32_sdwa v136, sext(v136) dst_sel:DWORD dst_unused:UNUSED_PAD src0_sel:WORD_0
	v_cvt_f32_i32_sdwa v147, sext(v139) dst_sel:DWORD dst_unused:UNUSED_PAD src0_sel:WORD_1
	v_cvt_f32_i32_sdwa v146, sext(v139) dst_sel:DWORD dst_unused:UNUSED_PAD src0_sel:WORD_0
	v_cvt_f32_i32_sdwa v139, sext(v138) dst_sel:DWORD dst_unused:UNUSED_PAD src0_sel:WORD_1
	v_cvt_f32_i32_sdwa v138, sext(v138) dst_sel:DWORD dst_unused:UNUSED_PAD src0_sel:WORD_0
	s_waitcnt vmcnt(0)
	v_cvt_f32_i32_sdwa v149, sext(v141) dst_sel:DWORD dst_unused:UNUSED_PAD src0_sel:WORD_1
	v_cvt_f32_i32_sdwa v148, sext(v141) dst_sel:DWORD dst_unused:UNUSED_PAD src0_sel:WORD_0
	v_cvt_f32_i32_sdwa v141, sext(v140) dst_sel:DWORD dst_unused:UNUSED_PAD src0_sel:WORD_1
	v_cvt_f32_i32_sdwa v140, sext(v140) dst_sel:DWORD dst_unused:UNUSED_PAD src0_sel:WORD_0
	v_cvt_f32_i32_sdwa v151, sext(v143) dst_sel:DWORD dst_unused:UNUSED_PAD src0_sel:WORD_1
	v_cvt_f32_i32_sdwa v150, sext(v143) dst_sel:DWORD dst_unused:UNUSED_PAD src0_sel:WORD_0
	v_cvt_f32_i32_sdwa v143, sext(v142) dst_sel:DWORD dst_unused:UNUSED_PAD src0_sel:WORD_1
	v_cvt_f32_i32_sdwa v142, sext(v142) dst_sel:DWORD dst_unused:UNUSED_PAD src0_sel:WORD_0
	v_pk_mul_f32 v[136:137], v[136:137], s[24:25] op_sel_hi:[1,0]
	v_pk_mul_f32 v[144:145], v[144:145], s[24:25] op_sel_hi:[1,0]
	v_pk_mul_f32 v[138:139], v[138:139], s[24:25] op_sel_hi:[1,0]
	v_pk_mul_f32 v[146:147], v[146:147], s[24:25] op_sel_hi:[1,0]
	v_pk_mul_f32 v[140:141], v[140:141], s[24:25] op_sel_hi:[1,0]
	v_pk_mul_f32 v[148:149], v[148:149], s[24:25] op_sel_hi:[1,0]
	v_pk_mul_f32 v[142:143], v[142:143], s[24:25] op_sel_hi:[1,0]
	v_pk_mul_f32 v[150:151], v[150:151], s[24:25] op_sel_hi:[1,0]
	v_pk_fma_f32 v[126:127], v[144:145], s[26:27], v[126:127] op_sel_hi:[1,0,1]
	v_pk_fma_f32 v[124:125], v[136:137], s[26:27], v[124:125] op_sel_hi:[1,0,1]
	v_pk_fma_f32 v[122:123], v[146:147], s[26:27], v[122:123] op_sel_hi:[1,0,1]
	v_pk_fma_f32 v[120:121], v[138:139], s[26:27], v[120:121] op_sel_hi:[1,0,1]
	v_pk_fma_f32 v[118:119], v[148:149], s[26:27], v[118:119] op_sel_hi:[1,0,1]
	v_pk_fma_f32 v[116:117], v[140:141], s[26:27], v[116:117] op_sel_hi:[1,0,1]
	v_pk_fma_f32 v[114:115], v[150:151], s[26:27], v[114:115] op_sel_hi:[1,0,1]
	v_pk_fma_f32 v[112:113], v[142:143], s[26:27], v[112:113] op_sel_hi:[1,0,1]
	s_nop 0
	s_and_saveexec_b64 s[0:1], vcc
	s_cbranch_execz .LBB0_1063
	v_mul_f32_e32 v136, 0x3c800000, v131
	s_waitcnt lgkmcnt(0)
	v_add_f32_e32 v137, v134, v135
	ds_write_b64 v130, v[136:137]
